# grid barrier: XCD leaders poll the TOP arrival counter directly (target (gen+1)*nx) instead of a separate TOPGEN flag; last leader no longer bumps TOPGEN
# speedup vs baseline: 1.0151x; 1.0033x over previous
.LBB0_135:
	s_or_b64 exec, exec, s[12:13]
	v_cvt_f32_u32_e32 v3, v0
	s_waitcnt vmcnt(0)
	v_readfirstlane_b32 s3, v2
	s_add_u32 s12, s22, 0x83400
	s_addc_u32 s13, s23, 0
	v_rcp_iflag_f32_e32 v3, v3
	v_add_u32_e32 v1, s3, v1
	v_add_u32_e32 v4, 1, v1
	s_mov_b64 s[14:15], 0
	v_mul_f32_e32 v2, 0x4f7ffffe, v3
	v_cvt_u32_f32_e32 v2, v2
	v_sub_u32_e32 v3, 0, v0
	v_mul_lo_u32 v3, v3, v2
	v_mul_hi_u32 v3, v2, v3
	v_add_u32_e32 v2, v2, v3
	v_mul_hi_u32 v2, v1, v2
	v_mul_lo_u32 v3, v2, v0
	v_sub_u32_e32 v1, v1, v3
	v_add_u32_e32 v5, 1, v2
	v_cmp_ge_u32_e32 vcc, v1, v0
	v_sub_u32_e32 v3, v1, v0
	s_nop 0
	v_cndmask_b32_e32 v2, v2, v5, vcc
	v_cndmask_b32_e32 v1, v1, v3, vcc
	v_add_u32_e32 v3, 1, v2
	v_cmp_ge_u32_e32 vcc, v1, v0
	s_nop 1
	v_cndmask_b32_e32 v2, v2, v3, vcc
	v_mul_lo_u32 v1, v0, v2
	v_add_u32_e32 v0, v1, v0
	v_cmp_ne_u32_e32 vcc, v4, v0
	v_mov_b32_e32 v6, v0
	v_mov_b64_e32 v[0:1], s[12:13]
	s_and_saveexec_b64 s[10:11], vcc
	s_cbranch_execz .LBB0_147
	v_mov_b32_e32 v0, 0
	global_load_dword v1, v0, s[12:13] sc1
	s_mov_b64 s[18:19], 0
	s_waitcnt vmcnt(0)
	v_cmp_lt_u32_e32 vcc, v1, v6
	s_and_saveexec_b64 s[16:17], vcc
	s_cbranch_execz .LBB0_146
	s_add_u32 s14, s22, 0x80200
	s_addc_u32 s15, s23, 0
	s_mov_b32 s3, 1
	s_branch .LBB0_139

.LBB0_141:
	global_load_dword v1, v0, s[12:13] sc1
	s_add_i32 s3, s3, 1
	s_mov_b64 s[28:29], -1
	s_waitcnt vmcnt(0)
	v_cmp_ge_u32_e32 vcc, v1, v6
	s_orn2_b64 s[34:35], vcc, exec
	s_branch .LBB0_138

.LBB0_197:
	s_or_b64 exec, exec, s[16:17]
	v_cvt_f32_u32_e32 v3, v0
	s_waitcnt vmcnt(0)
	v_readfirstlane_b32 s3, v2
	s_add_u32 s16, s22, 0x83400
	s_addc_u32 s17, s23, 0
	v_rcp_iflag_f32_e32 v3, v3
	v_add_u32_e32 v1, s3, v1
	v_add_u32_e32 v4, 1, v1
	s_mov_b64 s[18:19], 0
	v_mul_f32_e32 v2, 0x4f7ffffe, v3
	v_cvt_u32_f32_e32 v2, v2
	v_sub_u32_e32 v3, 0, v0
	v_mul_lo_u32 v3, v3, v2
	v_mul_hi_u32 v3, v2, v3
	v_add_u32_e32 v2, v2, v3
	v_mul_hi_u32 v2, v1, v2
	v_mul_lo_u32 v3, v2, v0
	v_sub_u32_e32 v1, v1, v3
	v_add_u32_e32 v5, 1, v2
	v_cmp_ge_u32_e32 vcc, v1, v0
	v_sub_u32_e32 v3, v1, v0
	s_nop 0
	v_cndmask_b32_e32 v2, v2, v5, vcc
	v_cndmask_b32_e32 v1, v1, v3, vcc
	v_add_u32_e32 v3, 1, v2
	v_cmp_ge_u32_e32 vcc, v1, v0
	s_nop 1
	v_cndmask_b32_e32 v2, v2, v3, vcc
	v_mul_lo_u32 v1, v0, v2
	v_add_u32_e32 v0, v1, v0
	v_cmp_ne_u32_e32 vcc, v4, v0
	v_mov_b32_e32 v6, v0
	v_mov_b64_e32 v[0:1], s[16:17]
	s_and_saveexec_b64 s[14:15], vcc
	s_cbranch_execz .LBB0_209
	v_mov_b32_e32 v0, 0
	global_load_dword v1, v0, s[16:17] sc1
	s_mov_b64 s[26:27], 0
	s_waitcnt vmcnt(0)
	v_cmp_lt_u32_e32 vcc, v1, v6
	s_and_saveexec_b64 s[20:21], vcc
	s_cbranch_execz .LBB0_208
	s_add_u32 s18, s22, 0x80200
	s_addc_u32 s19, s23, 0
	s_mov_b32 s3, 1
	s_branch .LBB0_201

.LBB0_203:
	global_load_dword v1, v0, s[16:17] sc1
	s_add_i32 s3, s3, 1
	s_mov_b64 s[30:31], -1
	s_waitcnt vmcnt(0)
	v_cmp_ge_u32_e32 vcc, v1, v6
	s_orn2_b64 s[36:37], vcc, exec
	s_branch .LBB0_200

.LBB0_732:
	s_or_b64 exec, exec, s[14:15]
	v_cvt_f32_u32_e32 v3, v0
	s_waitcnt vmcnt(0)
	v_readfirstlane_b32 s3, v2
	s_add_u32 s14, s22, 0x83400
	s_addc_u32 s15, s23, 0
	v_rcp_iflag_f32_e32 v3, v3
	v_add_u32_e32 v1, s3, v1
	v_add_u32_e32 v4, 1, v1
	s_mov_b64 s[18:19], 0
	v_mul_f32_e32 v2, 0x4f7ffffe, v3
	v_cvt_u32_f32_e32 v2, v2
	v_sub_u32_e32 v3, 0, v0
	v_mul_lo_u32 v3, v3, v2
	v_mul_hi_u32 v3, v2, v3
	v_add_u32_e32 v2, v2, v3
	v_mul_hi_u32 v2, v1, v2
	v_mul_lo_u32 v3, v2, v0
	v_sub_u32_e32 v1, v1, v3
	v_add_u32_e32 v5, 1, v2
	v_cmp_ge_u32_e32 vcc, v1, v0
	v_sub_u32_e32 v3, v1, v0
	s_nop 0
	v_cndmask_b32_e32 v2, v2, v5, vcc
	v_cndmask_b32_e32 v1, v1, v3, vcc
	v_add_u32_e32 v3, 1, v2
	v_cmp_ge_u32_e32 vcc, v1, v0
	s_nop 1
	v_cndmask_b32_e32 v2, v2, v3, vcc
	v_mul_lo_u32 v1, v0, v2
	v_add_u32_e32 v0, v1, v0
	v_cmp_ne_u32_e32 vcc, v4, v0
	v_mov_b32_e32 v6, v0
	v_mov_b64_e32 v[0:1], s[14:15]
	s_and_saveexec_b64 s[12:13], vcc
	s_cbranch_execz .LBB0_744
	v_mov_b32_e32 v0, 0
	global_load_dword v1, v0, s[14:15] sc1
	s_mov_b64 s[26:27], 0
	s_waitcnt vmcnt(0)
	v_cmp_lt_u32_e32 vcc, v1, v6
	s_and_saveexec_b64 s[20:21], vcc
	s_cbranch_execz .LBB0_743
	s_add_u32 s18, s22, 0x80200
	s_addc_u32 s19, s23, 0
	s_mov_b32 s3, 1
	s_branch .LBB0_736

.LBB0_738:
	global_load_dword v1, v0, s[14:15] sc1
	s_add_i32 s3, s3, 1
	s_mov_b64 s[30:31], -1
	s_waitcnt vmcnt(0)
	v_cmp_ge_u32_e32 vcc, v1, v6
	s_orn2_b64 s[36:37], vcc, exec
	s_branch .LBB0_735

.LBB0_1078:
	s_or_b64 exec, exec, s[14:15]
	v_cvt_f32_u32_e32 v3, v0
	s_waitcnt vmcnt(0)
	v_readfirstlane_b32 s3, v2
	s_add_u32 s14, s22, 0x83400
	s_addc_u32 s15, s23, 0
	v_rcp_iflag_f32_e32 v3, v3
	v_add_u32_e32 v1, s3, v1
	v_add_u32_e32 v4, 1, v1
	s_mov_b64 s[16:17], 0
	v_mul_f32_e32 v2, 0x4f7ffffe, v3
	v_cvt_u32_f32_e32 v2, v2
	v_sub_u32_e32 v3, 0, v0
	v_mul_lo_u32 v3, v3, v2
	v_mul_hi_u32 v3, v2, v3
	v_add_u32_e32 v2, v2, v3
	v_mul_hi_u32 v2, v1, v2
	v_mul_lo_u32 v3, v2, v0
	v_sub_u32_e32 v1, v1, v3
	v_add_u32_e32 v5, 1, v2
	v_cmp_ge_u32_e32 vcc, v1, v0
	v_sub_u32_e32 v3, v1, v0
	s_nop 0
	v_cndmask_b32_e32 v2, v2, v5, vcc
	v_cndmask_b32_e32 v1, v1, v3, vcc
	v_add_u32_e32 v3, 1, v2
	v_cmp_ge_u32_e32 vcc, v1, v0
	s_nop 1
	v_cndmask_b32_e32 v2, v2, v3, vcc
	v_mul_lo_u32 v1, v0, v2
	v_add_u32_e32 v0, v1, v0
	v_cmp_ne_u32_e32 vcc, v4, v0
	v_mov_b32_e32 v6, v0
	v_mov_b64_e32 v[0:1], s[14:15]
	s_and_saveexec_b64 s[10:11], vcc
	s_cbranch_execz .LBB0_1090
	v_mov_b32_e32 v0, 0
	global_load_dword v1, v0, s[14:15] sc1
	s_mov_b64 s[20:21], 0
	s_waitcnt vmcnt(0)
	v_cmp_lt_u32_e32 vcc, v1, v6
	s_and_saveexec_b64 s[18:19], vcc
	s_cbranch_execz .LBB0_1089
	s_add_u32 s16, s22, 0x80200
	s_addc_u32 s17, s23, 0
	s_mov_b32 s3, 1
	s_branch .LBB0_1082

.LBB0_1084:
	global_load_dword v1, v0, s[14:15] sc1
	s_add_i32 s3, s3, 1
	s_mov_b64 s[28:29], -1
	s_waitcnt vmcnt(0)
	v_cmp_ge_u32_e32 vcc, v1, v6
	s_orn2_b64 s[34:35], vcc, exec
	s_branch .LBB0_1081

.LBB0_1383:
	s_or_b64 exec, exec, s[14:15]
	v_cvt_f32_u32_e32 v3, v0
	s_waitcnt vmcnt(0)
	v_readfirstlane_b32 s3, v2
	s_add_u32 s14, s22, 0x83400
	s_addc_u32 s15, s23, 0
	v_rcp_iflag_f32_e32 v3, v3
	v_add_u32_e32 v1, s3, v1
	v_add_u32_e32 v4, 1, v1
	s_mov_b64 s[16:17], 0
	v_mul_f32_e32 v2, 0x4f7ffffe, v3
	v_cvt_u32_f32_e32 v2, v2
	v_sub_u32_e32 v3, 0, v0
	v_mul_lo_u32 v3, v3, v2
	v_mul_hi_u32 v3, v2, v3
	v_add_u32_e32 v2, v2, v3
	v_mul_hi_u32 v2, v1, v2
	v_mul_lo_u32 v3, v2, v0
	v_sub_u32_e32 v1, v1, v3
	v_add_u32_e32 v5, 1, v2
	v_cmp_ge_u32_e32 vcc, v1, v0
	v_sub_u32_e32 v3, v1, v0
	s_nop 0
	v_cndmask_b32_e32 v2, v2, v5, vcc
	v_cndmask_b32_e32 v1, v1, v3, vcc
	v_add_u32_e32 v3, 1, v2
	v_cmp_ge_u32_e32 vcc, v1, v0
	s_nop 1
	v_cndmask_b32_e32 v2, v2, v3, vcc
	v_mul_lo_u32 v1, v0, v2
	v_add_u32_e32 v0, v1, v0
	v_cmp_ne_u32_e32 vcc, v4, v0
	v_mov_b32_e32 v6, v0
	v_mov_b64_e32 v[0:1], s[14:15]
	s_and_saveexec_b64 s[12:13], vcc
	s_cbranch_execz .LBB0_1395
	v_mov_b32_e32 v0, 0
	global_load_dword v1, v0, s[14:15] sc1
	s_mov_b64 s[26:27], 0
	s_waitcnt vmcnt(0)
	v_cmp_lt_u32_e32 vcc, v1, v6
	s_and_saveexec_b64 s[18:19], vcc
	s_cbranch_execz .LBB0_1394
	s_add_u32 s16, s22, 0x80200
	s_addc_u32 s17, s23, 0
	s_mov_b32 s3, 1
	s_branch .LBB0_1387

.LBB0_1567:
	s_or_b64 exec, exec, s[4:5]
	v_cvt_f32_u32_e32 v3, v0
	s_waitcnt vmcnt(0)
	v_readfirstlane_b32 s2, v2
	s_add_u32 s4, s22, 0x83400
	s_addc_u32 s5, s23, 0
	v_rcp_iflag_f32_e32 v3, v3
	v_add_u32_e32 v1, s2, v1
	v_add_u32_e32 v4, 1, v1
	s_mov_b64 s[6:7], 0
	v_mul_f32_e32 v2, 0x4f7ffffe, v3
	v_cvt_u32_f32_e32 v2, v2
	v_sub_u32_e32 v3, 0, v0
	v_mul_lo_u32 v3, v3, v2
	v_mul_hi_u32 v3, v2, v3
	v_add_u32_e32 v2, v2, v3
	v_mul_hi_u32 v2, v1, v2
	v_mul_lo_u32 v3, v2, v0
	v_sub_u32_e32 v1, v1, v3
	v_add_u32_e32 v5, 1, v2
	v_cmp_ge_u32_e32 vcc, v1, v0
	v_sub_u32_e32 v3, v1, v0
	s_nop 0
	v_cndmask_b32_e32 v2, v2, v5, vcc
	v_cndmask_b32_e32 v1, v1, v3, vcc
	v_add_u32_e32 v3, 1, v2
	v_cmp_ge_u32_e32 vcc, v1, v0
	s_nop 1
	v_cndmask_b32_e32 v2, v2, v3, vcc
	v_mul_lo_u32 v1, v0, v2
	v_add_u32_e32 v0, v1, v0
	v_cmp_ne_u32_e32 vcc, v4, v0
	v_mov_b32_e32 v6, v0
	v_mov_b64_e32 v[0:1], s[4:5]
	s_and_saveexec_b64 s[2:3], vcc
	s_cbranch_execz .LBB0_1579
	v_mov_b32_e32 v0, 0
	global_load_dword v1, v0, s[4:5] sc1
	s_mov_b64 s[10:11], 0
	s_waitcnt vmcnt(0)
	v_cmp_lt_u32_e32 vcc, v1, v6
	s_and_saveexec_b64 s[8:9], vcc
	s_cbranch_execz .LBB0_1578
	s_add_u32 s6, s22, 0x80200
	s_addc_u32 s7, s23, 0
	s_mov_b32 s20, 1
	s_branch .LBB0_1571

.LBB0_1573:
	global_load_dword v1, v0, s[4:5] sc1
	s_add_i32 s20, s20, 1
	s_mov_b64 s[14:15], -1
	s_waitcnt vmcnt(0)
	v_cmp_ge_u32_e32 vcc, v1, v6
	s_orn2_b64 s[18:19], vcc, exec
	s_branch .LBB0_1570
